# phase_norm: issue the four row loads together (one memory round trip per row instead of two)
# speedup vs baseline: 1.4140x; 1.0119x over previous
; DI unsigned pack2(float a, float b) { f2_t v = {a, b}; bf2_t r = __builtin_convertvector(v, bf2_t); return __builtin_bit_cast(unsigned, r); }
; DI float wave_sum(float v) { for (int o = 32; o > 0; o >>= 1) v += __shfl_xor(v, o); return v; }
; DI void rms_row_bf16(const float* __restrict__ src, const float* __restrict__ g, u16* __restrict__ dst, int lane) {
;   float4 v[4]; float ss = 0.f;
; #pragma unroll
;   for (int i = 0; i < 4; ++i) { v[i] = *(const float4*)(src + i * 256 + lane * 4); ss += v[i].x * v[i].x + v[i].y * v[i].y + v[i].z * v[i].z + v[i].w * v[i].w; }
;   ss = wave_sum(ss);
;   float rs = rsqrtf(ss * (1.f / 1024.f) + 1e-6f);
; #pragma unroll
;   for (int i = 0; i < 4; ++i) {
;     float4 gg = *(const float4*)(g + i * 256 + lane * 4);
;     uint2 o; o.x = pack2(v[i].x * rs * gg.x, v[i].y * rs * gg.y); o.y = pack2(v[i].z * rs * gg.z, v[i].w * rs * gg.w);
;     *(uint2*)(dst + i * 256 + lane * 4) = o;
;   }
; }
; DI void phase_norm(const Params& p, int L, int c) {
;     ...
;   for (int lr = blockIdx.x * 4 + w; lr < TC; lr += gridDim.x * 4) {
;     int gt = gtok(rw, c, lr);
;     rms_row_bf16(xs + (size_t)gt * 1024, p.norm_g + L * 1024, H + (size_t)lr * 1024, lane);
;   }
.LBB0_89:
	v_ashrrev_i32_e32 v23, 31, v22
	v_lshlrev_b64 v[22:23], 12, v[22:23]
	v_ashrrev_i32_e32 v17, 31, v16
	v_lshlrev_b64 v[32:33], 11, v[16:17]
	v_lshl_add_u64 v[22:23], v[18:19], 0, v[22:23]
	v_lshl_add_u64 v[48:49], v[20:21], 0, v[32:33]
	global_load_dwordx4 v[32:35], v[22:23], off
	global_load_dwordx4 v[36:39], v[22:23], off offset:1024
	global_load_dwordx4 v[40:43], v[22:23], off offset:2048
	global_load_dwordx4 v[44:47], v[22:23], off offset:3072
	s_mov_b32 s8, 0x800000
	s_waitcnt vmcnt(3)
	v_pk_mul_f32 v[50:51], v[32:33], v[32:33]
	v_pk_mul_f32 v[52:53], v[34:35], v[34:35]
	s_waitcnt vmcnt(2)
	v_pk_fma_f32 v[50:51], v[36:37], v[36:37], v[50:51]
	v_pk_fma_f32 v[52:53], v[38:39], v[38:39], v[52:53]
	s_waitcnt vmcnt(1)
	v_pk_fma_f32 v[50:51], v[40:41], v[40:41], v[50:51]
	v_pk_fma_f32 v[52:53], v[42:43], v[42:43], v[52:53]
	s_waitcnt vmcnt(0)
	v_pk_fma_f32 v[50:51], v[44:45], v[44:45], v[50:51]
	v_pk_fma_f32 v[52:53], v[46:47], v[46:47], v[52:53]
	s_nop 0
	v_pk_add_f32 v[50:51], v[50:51], v[52:53]
	s_nop 0
	v_add_f32_e32 v17, v50, v51
	ds_bpermute_b32 v22, v24, v17
	s_waitcnt lgkmcnt(0)
	v_add_f32_e32 v17, v17, v22
	ds_bpermute_b32 v22, v25, v17
	s_waitcnt lgkmcnt(0)
	v_add_f32_e32 v17, v17, v22
	ds_bpermute_b32 v22, v26, v17
	s_waitcnt lgkmcnt(0)
	v_add_f32_e32 v17, v17, v22
	ds_bpermute_b32 v22, v27, v17
	s_waitcnt lgkmcnt(0)
	v_add_f32_e32 v17, v17, v22
	ds_bpermute_b32 v22, v28, v17
	s_waitcnt lgkmcnt(0)
	v_add_f32_e32 v17, v17, v22
	ds_bpermute_b32 v22, v29, v17
	s_waitcnt lgkmcnt(0)
	v_add_f32_e32 v17, v17, v22
	v_fmamk_f32 v17, v17, 0x3a800000, v206
	v_cmp_gt_f32_e32 vcc, s8, v17
	v_mul_f32_e32 v22, 0x4b800000, v17
	v_readlane_b32 s8, v254, 18
	v_cndmask_b32_e32 v17, v17, v22, vcc
	v_rsq_f32_e32 v17, v17
	v_add_u32_e32 v16, s8, v16
	v_readlane_b32 s8, v253, 51
	v_readlane_b32 s9, v254, 19
	v_mul_f32_e32 v22, 0x45800000, v17
	v_cndmask_b32_e32 v22, v17, v22, vcc
	v_pk_mul_f32 v[32:33], v[32:33], v[22:23] op_sel_hi:[1,0]
	v_pk_mul_f32 v[34:35], v[34:35], v[22:23] op_sel_hi:[1,0]
	v_pk_mul_f32 v[32:33], v[0:1], v[32:33]
	v_pk_mul_f32 v[34:35], v[2:3], v[34:35]
	v_cvt_pk_bf16_f32 v32, v32, v33
	v_cvt_pk_bf16_f32 v33, v34, v35
	global_store_dwordx2 v[48:49], v[32:33], off
	v_pk_mul_f32 v[32:33], v[36:37], v[22:23] op_sel_hi:[1,0]
	v_pk_mul_f32 v[34:35], v[38:39], v[22:23] op_sel_hi:[1,0]
	v_pk_mul_f32 v[32:33], v[4:5], v[32:33]
	v_pk_mul_f32 v[34:35], v[6:7], v[34:35]
	v_cvt_pk_bf16_f32 v32, v32, v33
	v_cvt_pk_bf16_f32 v33, v34, v35
	global_store_dwordx2 v[48:49], v[32:33], off offset:512
	v_pk_mul_f32 v[32:33], v[40:41], v[22:23] op_sel_hi:[1,0]
	v_pk_mul_f32 v[34:35], v[42:43], v[22:23] op_sel_hi:[1,0]
	v_pk_mul_f32 v[32:33], v[32:33], v[8:9]
	v_pk_mul_f32 v[34:35], v[34:35], v[10:11]
	v_cvt_pk_bf16_f32 v32, v32, v33
	v_cvt_pk_bf16_f32 v33, v34, v35
	global_store_dwordx2 v[48:49], v[32:33], off offset:1024
	v_pk_mul_f32 v[32:33], v[44:45], v[22:23] op_sel_hi:[1,0]
	v_pk_mul_f32 v[22:23], v[46:47], v[22:23] op_sel_hi:[1,0]
	v_add_u32_e32 v30, s8, v30
	s_movk_i32 s8, 0x3fff
	v_pk_mul_f32 v[32:33], v[32:33], v[12:13]
	v_pk_mul_f32 v[22:23], v[22:23], v[14:15]
	v_cmp_lt_i32_e32 vcc, s8, v16
	v_cvt_pk_bf16_f32 v32, v32, v33
	v_cvt_pk_bf16_f32 v33, v22, v23
	s_or_b64 s[6:7], vcc, s[6:7]
	global_store_dwordx2 v[48:49], v[32:33], off offset:1536
	s_andn2_b64 exec, exec, s[6:7]
	s_cbranch_execz .LBB0_94

; DI unsigned pack2(float a, float b) { f2_t v = {a, b}; bf2_t r = __builtin_convertvector(v, bf2_t); return __builtin_bit_cast(unsigned, r); }
; DI float wave_sum(float v) { for (int o = 32; o > 0; o >>= 1) v += __shfl_xor(v, o); return v; }
; DI void rms_row_bf16(const float* __restrict__ src, const float* __restrict__ g, u16* __restrict__ dst, int lane) {
;   float4 v[4]; float ss = 0.f;
; #pragma unroll
;   for (int i = 0; i < 4; ++i) { v[i] = *(const float4*)(src + i * 256 + lane * 4); ss += v[i].x * v[i].x + v[i].y * v[i].y + v[i].z * v[i].z + v[i].w * v[i].w; }
;   ss = wave_sum(ss);
;   float rs = rsqrtf(ss * (1.f / 1024.f) + 1e-6f);
; #pragma unroll
;   for (int i = 0; i < 4; ++i) {
;     float4 gg = *(const float4*)(g + i * 256 + lane * 4);
;     uint2 o; o.x = pack2(v[i].x * rs * gg.x, v[i].y * rs * gg.y); o.y = pack2(v[i].z * rs * gg.z, v[i].w * rs * gg.w);
;     *(uint2*)(dst + i * 256 + lane * 4) = o;
;   }
; }
; DI void phase_norm(const Params& p, int L, int c) {
;     ...
;   for (int lr = blockIdx.x * 4 + w; lr < TC; lr += gridDim.x * 4) {
;     int gt = gtok(rw, c, lr);
;     rms_row_bf16(xs + (size_t)gt * 1024, p.norm_g + L * 1024, H + (size_t)lr * 1024, lane);
;   }
.LBB0_618:
	v_ashrrev_i32_e32 v23, 31, v22
	v_lshlrev_b64 v[22:23], 12, v[22:23]
	v_ashrrev_i32_e32 v17, 31, v16
	v_lshlrev_b64 v[32:33], 11, v[16:17]
	v_lshl_add_u64 v[22:23], v[18:19], 0, v[22:23]
	v_lshl_add_u64 v[48:49], v[20:21], 0, v[32:33]
	global_load_dwordx4 v[32:35], v[22:23], off
	global_load_dwordx4 v[36:39], v[22:23], off offset:1024
	global_load_dwordx4 v[40:43], v[22:23], off offset:2048
	global_load_dwordx4 v[44:47], v[22:23], off offset:3072
	s_mov_b32 s8, 0x800000
	v_add_u32_e32 v16, s26, v16
	s_waitcnt vmcnt(3)
	v_pk_mul_f32 v[50:51], v[32:33], v[32:33]
	v_pk_mul_f32 v[52:53], v[34:35], v[34:35]
	s_waitcnt vmcnt(2)
	v_pk_fma_f32 v[50:51], v[36:37], v[36:37], v[50:51]
	v_pk_fma_f32 v[52:53], v[38:39], v[38:39], v[52:53]
	s_waitcnt vmcnt(1)
	v_pk_fma_f32 v[50:51], v[40:41], v[40:41], v[50:51]
	v_pk_fma_f32 v[52:53], v[42:43], v[42:43], v[52:53]
	s_waitcnt vmcnt(0)
	v_pk_fma_f32 v[50:51], v[44:45], v[44:45], v[50:51]
	v_pk_fma_f32 v[52:53], v[46:47], v[46:47], v[52:53]
	s_nop 0
	v_pk_add_f32 v[50:51], v[50:51], v[52:53]
	s_nop 0
	v_add_f32_e32 v17, v50, v51
	ds_bpermute_b32 v22, v24, v17
	s_waitcnt lgkmcnt(0)
	v_add_f32_e32 v17, v17, v22
	ds_bpermute_b32 v22, v25, v17
	s_waitcnt lgkmcnt(0)
	v_add_f32_e32 v17, v17, v22
	ds_bpermute_b32 v22, v26, v17
	s_waitcnt lgkmcnt(0)
	v_add_f32_e32 v17, v17, v22
	ds_bpermute_b32 v22, v27, v17
	s_waitcnt lgkmcnt(0)
	v_add_f32_e32 v17, v17, v22
	ds_bpermute_b32 v22, v28, v17
	s_waitcnt lgkmcnt(0)
	v_add_f32_e32 v17, v17, v22
	ds_bpermute_b32 v22, v29, v17
	s_waitcnt lgkmcnt(0)
	v_add_f32_e32 v17, v17, v22
	v_fmamk_f32 v17, v17, 0x3a800000, v206
	v_cmp_gt_f32_e32 vcc, s8, v17
	v_mul_f32_e32 v22, 0x4b800000, v17
	v_readlane_b32 s8, v253, 51
	v_cndmask_b32_e32 v17, v17, v22, vcc
	v_rsq_f32_e32 v17, v17
	v_add_u32_e32 v30, s8, v30
	s_movk_i32 s8, 0x3fff
	v_mul_f32_e32 v22, 0x45800000, v17
	v_cndmask_b32_e32 v22, v17, v22, vcc
	v_pk_mul_f32 v[32:33], v[32:33], v[22:23] op_sel_hi:[1,0]
	v_pk_mul_f32 v[34:35], v[34:35], v[22:23] op_sel_hi:[1,0]
	v_pk_mul_f32 v[32:33], v[0:1], v[32:33]
	v_pk_mul_f32 v[34:35], v[2:3], v[34:35]
	v_cvt_pk_bf16_f32 v32, v32, v33
	v_cvt_pk_bf16_f32 v33, v34, v35
	global_store_dwordx2 v[48:49], v[32:33], off
	v_pk_mul_f32 v[32:33], v[36:37], v[22:23] op_sel_hi:[1,0]
	v_pk_mul_f32 v[34:35], v[38:39], v[22:23] op_sel_hi:[1,0]
	v_pk_mul_f32 v[32:33], v[4:5], v[32:33]
	v_pk_mul_f32 v[34:35], v[6:7], v[34:35]
	v_cvt_pk_bf16_f32 v32, v32, v33
	v_cvt_pk_bf16_f32 v33, v34, v35
	global_store_dwordx2 v[48:49], v[32:33], off offset:512
	v_pk_mul_f32 v[32:33], v[40:41], v[22:23] op_sel_hi:[1,0]
	v_pk_mul_f32 v[34:35], v[42:43], v[22:23] op_sel_hi:[1,0]
	v_pk_mul_f32 v[32:33], v[32:33], v[8:9]
	v_pk_mul_f32 v[34:35], v[34:35], v[10:11]
	v_cvt_pk_bf16_f32 v32, v32, v33
	v_cvt_pk_bf16_f32 v33, v34, v35
	global_store_dwordx2 v[48:49], v[32:33], off offset:1024
	v_pk_mul_f32 v[32:33], v[44:45], v[22:23] op_sel_hi:[1,0]
	v_pk_mul_f32 v[22:23], v[46:47], v[22:23] op_sel_hi:[1,0]
	v_pk_mul_f32 v[32:33], v[32:33], v[12:13]
	v_pk_mul_f32 v[22:23], v[22:23], v[14:15]
	v_cmp_lt_i32_e32 vcc, s8, v16
	v_cvt_pk_bf16_f32 v32, v32, v33
	v_cvt_pk_bf16_f32 v33, v22, v23
	s_or_b64 s[6:7], vcc, s[6:7]
	global_store_dwordx2 v[48:49], v[32:33], off offset:1536
	s_andn2_b64 exec, exec, s[6:7]
	s_cbranch_execz .LBB0_623
